# y stores moved behind the row-sum exchange into step 5 + batched K-split part fold in ctx norm
# speedup vs baseline: 1.0497x; 1.0115x over previous
.LBB0_384:
	s_or_b64 exec, exec, s[28:29]
	s_lshr_b32 s100, s22, 3
	s_mul_i32 s100, s100, 0x9000
	s_and_b64 vcc, exec, s[10:11]
	s_cselect_b32 s100, s100, 0
	s_cselect_b32 s101, 0x1000, 0
	v_add_u32_e32 v225, s101, v222
	s_add_u32 s100, s24, s100
	s_addc_u32 s101, s25, 0
	global_load_dwordx4 v[156:159], v222, s[100:101]
	global_load_dwordx4 v[160:163], v222, s[100:101] offset:64
	global_load_dwordx4 v[164:167], v222, s[100:101] offset:512
	global_load_dwordx4 v[168:171], v222, s[100:101] offset:576
	global_load_dwordx4 v[172:175], v225, s[100:101]
	global_load_dwordx4 v[176:179], v225, s[100:101] offset:64
	global_load_dwordx4 v[180:183], v225, s[100:101] offset:512
	global_load_dwordx4 v[184:187], v225, s[100:101] offset:576
	s_cmp_gt_u32 s23, 63
	s_cbranch_scc1 .LBB0_394
	s_lshl_b32 s8, s22, 4
	s_ashr_i32 s9, s8, 31
	s_lshl_b64 s[8:9], s[8:9], 2
	s_add_u32 s28, s21, s8
	s_addc_u32 s29, s39, s9
	s_mov_b32 s21, 0x400001
	s_branch .LBB0_387

.LBB0_396:
	s_or_b64 exec, exec, s[28:29]
	s_ashr_i32 s23, s22, 31
	s_lshl_b64 s[0:1], s[22:23], 20
	s_add_u32 s8, s16, s0
	s_waitcnt vmcnt(0) lgkmcnt(0)
	s_barrier
	s_addc_u32 s9, s17, s1
	ds_read_b32 v188, v221 offset:16384
	ds_read_b32 v190, v221 offset:16448
	ds_read_b32 v192, v221 offset:16512
	ds_read_b32 v194, v221 offset:16576
	ds_read_b32 v196, v221 offset:16896
	ds_read_b32 v198, v221 offset:16960
	ds_read_b32 v200, v221 offset:17024
	ds_read_b32 v202, v221 offset:17088
	s_and_b64 vcc, exec, s[10:11]
	s_cbranch_vccz .Lepi_final_down
	s_add_u32 s100, s26, 0x3100000
	s_addc_u32 s101, s27, 0
	v_lshrrev_b32_e32 v224, 1, v220
	v_pk_add_f32 v[172:173], v[172:173], 1.0 op_sel_hi:[1,0]
	v_pk_add_f32 v[174:175], v[174:175], 1.0 op_sel_hi:[1,0]
	v_pk_add_f32 v[176:177], v[176:177], 1.0 op_sel_hi:[1,0]
	v_pk_add_f32 v[178:179], v[178:179], 1.0 op_sel_hi:[1,0]
	v_pk_add_f32 v[180:181], v[180:181], 1.0 op_sel_hi:[1,0]
	v_pk_add_f32 v[182:183], v[182:183], 1.0 op_sel_hi:[1,0]
	v_pk_add_f32 v[184:185], v[184:185], 1.0 op_sel_hi:[1,0]
	v_pk_add_f32 v[186:187], v[186:187], 1.0 op_sel_hi:[1,0]
	s_waitcnt lgkmcnt(0)
	v_mov_b32_e32 v225, v220
	global_store_dwordx4 v225, v[128:131], s[16:17]
	global_store_dwordx4 v225, v[124:127], s[16:17] offset:64
	global_store_dwordx4 v225, v[120:123], s[16:17] offset:512
	global_store_dwordx4 v225, v[116:119], s[16:17] offset:576
	v_add_u32_e32 v225, 0x10000, v225
	v_pk_mul_f32 v[132:133], v[128:129], v[188:189] op_sel_hi:[1,0]
	v_pk_mul_f32 v[134:135], v[130:131], v[188:189] op_sel_hi:[1,0]
	v_pk_fma_f32 v[132:133], v[172:173], v[132:133], v[156:157]
	v_pk_fma_f32 v[134:135], v[174:175], v[134:135], v[158:159]
	v_cvt_pk_bf16_f32 v132, v132, v133
	v_cvt_pk_bf16_f32 v133, v134, v135
	global_store_dwordx2 v224, v[132:133], s[100:101]
	v_pk_mul_f32 v[136:137], v[124:125], v[188:189] op_sel_hi:[1,0]
	v_pk_mul_f32 v[138:139], v[126:127], v[188:189] op_sel_hi:[1,0]
	v_pk_fma_f32 v[136:137], v[176:177], v[136:137], v[160:161]
	v_pk_fma_f32 v[138:139], v[178:179], v[138:139], v[162:163]
	v_cvt_pk_bf16_f32 v136, v136, v137
	v_cvt_pk_bf16_f32 v137, v138, v139
	global_store_dwordx2 v224, v[136:137], s[100:101] offset:32
	v_pk_mul_f32 v[140:141], v[120:121], v[188:189] op_sel_hi:[1,0]
	v_pk_mul_f32 v[142:143], v[122:123], v[188:189] op_sel_hi:[1,0]
	v_pk_fma_f32 v[140:141], v[180:181], v[140:141], v[164:165]
	v_pk_fma_f32 v[142:143], v[182:183], v[142:143], v[166:167]
	v_cvt_pk_bf16_f32 v140, v140, v141
	v_cvt_pk_bf16_f32 v141, v142, v143
	global_store_dwordx2 v224, v[140:141], s[100:101] offset:256
	v_pk_mul_f32 v[144:145], v[116:117], v[188:189] op_sel_hi:[1,0]
	v_pk_mul_f32 v[146:147], v[118:119], v[188:189] op_sel_hi:[1,0]
	v_pk_fma_f32 v[144:145], v[184:185], v[144:145], v[168:169]
	v_pk_fma_f32 v[146:147], v[186:187], v[146:147], v[170:171]
	v_cvt_pk_bf16_f32 v144, v144, v145
	v_cvt_pk_bf16_f32 v145, v146, v147
	global_store_dwordx2 v224, v[144:145], s[100:101] offset:288
	v_add_u32_e32 v224, 0x8000, v224
	global_store_dwordx4 v225, v[112:115], s[16:17]
	global_store_dwordx4 v225, v[108:111], s[16:17] offset:64
	global_store_dwordx4 v225, v[104:107], s[16:17] offset:512
	global_store_dwordx4 v225, v[100:103], s[16:17] offset:576
	v_add_u32_e32 v225, 0x10000, v225
	v_pk_mul_f32 v[132:133], v[112:113], v[190:191] op_sel_hi:[1,0]
	v_pk_mul_f32 v[134:135], v[114:115], v[190:191] op_sel_hi:[1,0]
	v_pk_fma_f32 v[132:133], v[172:173], v[132:133], v[156:157]
	v_pk_fma_f32 v[134:135], v[174:175], v[134:135], v[158:159]
	v_cvt_pk_bf16_f32 v132, v132, v133
	v_cvt_pk_bf16_f32 v133, v134, v135
	global_store_dwordx2 v224, v[132:133], s[100:101]
	v_pk_mul_f32 v[136:137], v[108:109], v[190:191] op_sel_hi:[1,0]
	v_pk_mul_f32 v[138:139], v[110:111], v[190:191] op_sel_hi:[1,0]
	v_pk_fma_f32 v[136:137], v[176:177], v[136:137], v[160:161]
	v_pk_fma_f32 v[138:139], v[178:179], v[138:139], v[162:163]
	v_cvt_pk_bf16_f32 v136, v136, v137
	v_cvt_pk_bf16_f32 v137, v138, v139
	global_store_dwordx2 v224, v[136:137], s[100:101] offset:32
	v_pk_mul_f32 v[140:141], v[104:105], v[190:191] op_sel_hi:[1,0]
	v_pk_mul_f32 v[142:143], v[106:107], v[190:191] op_sel_hi:[1,0]
	v_pk_fma_f32 v[140:141], v[180:181], v[140:141], v[164:165]
	v_pk_fma_f32 v[142:143], v[182:183], v[142:143], v[166:167]
	v_cvt_pk_bf16_f32 v140, v140, v141
	v_cvt_pk_bf16_f32 v141, v142, v143
	global_store_dwordx2 v224, v[140:141], s[100:101] offset:256
	v_pk_mul_f32 v[144:145], v[100:101], v[190:191] op_sel_hi:[1,0]
	v_pk_mul_f32 v[146:147], v[102:103], v[190:191] op_sel_hi:[1,0]
	v_pk_fma_f32 v[144:145], v[184:185], v[144:145], v[168:169]
	v_pk_fma_f32 v[146:147], v[186:187], v[146:147], v[170:171]
	v_cvt_pk_bf16_f32 v144, v144, v145
	v_cvt_pk_bf16_f32 v145, v146, v147
	global_store_dwordx2 v224, v[144:145], s[100:101] offset:288
	v_add_u32_e32 v224, 0x8000, v224
	global_store_dwordx4 v225, v[96:99], s[16:17]
	global_store_dwordx4 v225, v[92:95], s[16:17] offset:64
	global_store_dwordx4 v225, v[88:91], s[16:17] offset:512
	global_store_dwordx4 v225, v[84:87], s[16:17] offset:576
	v_add_u32_e32 v225, 0x10000, v225
	v_pk_mul_f32 v[132:133], v[96:97], v[192:193] op_sel_hi:[1,0]
	v_pk_mul_f32 v[134:135], v[98:99], v[192:193] op_sel_hi:[1,0]
	v_pk_fma_f32 v[132:133], v[172:173], v[132:133], v[156:157]
	v_pk_fma_f32 v[134:135], v[174:175], v[134:135], v[158:159]
	v_cvt_pk_bf16_f32 v132, v132, v133
	v_cvt_pk_bf16_f32 v133, v134, v135
	global_store_dwordx2 v224, v[132:133], s[100:101]
	v_pk_mul_f32 v[136:137], v[92:93], v[192:193] op_sel_hi:[1,0]
	v_pk_mul_f32 v[138:139], v[94:95], v[192:193] op_sel_hi:[1,0]
	v_pk_fma_f32 v[136:137], v[176:177], v[136:137], v[160:161]
	v_pk_fma_f32 v[138:139], v[178:179], v[138:139], v[162:163]
	v_cvt_pk_bf16_f32 v136, v136, v137
	v_cvt_pk_bf16_f32 v137, v138, v139
	global_store_dwordx2 v224, v[136:137], s[100:101] offset:32
	v_pk_mul_f32 v[140:141], v[88:89], v[192:193] op_sel_hi:[1,0]
	v_pk_mul_f32 v[142:143], v[90:91], v[192:193] op_sel_hi:[1,0]
	v_pk_fma_f32 v[140:141], v[180:181], v[140:141], v[164:165]
	v_pk_fma_f32 v[142:143], v[182:183], v[142:143], v[166:167]
	v_cvt_pk_bf16_f32 v140, v140, v141
	v_cvt_pk_bf16_f32 v141, v142, v143
	global_store_dwordx2 v224, v[140:141], s[100:101] offset:256
	v_pk_mul_f32 v[144:145], v[84:85], v[192:193] op_sel_hi:[1,0]
	v_pk_mul_f32 v[146:147], v[86:87], v[192:193] op_sel_hi:[1,0]
	v_pk_fma_f32 v[144:145], v[184:185], v[144:145], v[168:169]
	v_pk_fma_f32 v[146:147], v[186:187], v[146:147], v[170:171]
	v_cvt_pk_bf16_f32 v144, v144, v145
	v_cvt_pk_bf16_f32 v145, v146, v147
	global_store_dwordx2 v224, v[144:145], s[100:101] offset:288
	v_add_u32_e32 v224, 0x8000, v224
	global_store_dwordx4 v225, v[80:83], s[16:17]
	global_store_dwordx4 v225, v[76:79], s[16:17] offset:64
	global_store_dwordx4 v225, v[72:75], s[16:17] offset:512
	global_store_dwordx4 v225, v[68:71], s[16:17] offset:576
	v_add_u32_e32 v225, 0x50000, v225
	v_pk_mul_f32 v[132:133], v[80:81], v[194:195] op_sel_hi:[1,0]
	v_pk_mul_f32 v[134:135], v[82:83], v[194:195] op_sel_hi:[1,0]
	v_pk_fma_f32 v[132:133], v[172:173], v[132:133], v[156:157]
	v_pk_fma_f32 v[134:135], v[174:175], v[134:135], v[158:159]
	v_cvt_pk_bf16_f32 v132, v132, v133
	v_cvt_pk_bf16_f32 v133, v134, v135
	global_store_dwordx2 v224, v[132:133], s[100:101]
	v_pk_mul_f32 v[136:137], v[76:77], v[194:195] op_sel_hi:[1,0]
	v_pk_mul_f32 v[138:139], v[78:79], v[194:195] op_sel_hi:[1,0]
	v_pk_fma_f32 v[136:137], v[176:177], v[136:137], v[160:161]
	v_pk_fma_f32 v[138:139], v[178:179], v[138:139], v[162:163]
	v_cvt_pk_bf16_f32 v136, v136, v137
	v_cvt_pk_bf16_f32 v137, v138, v139
	global_store_dwordx2 v224, v[136:137], s[100:101] offset:32
	v_pk_mul_f32 v[140:141], v[72:73], v[194:195] op_sel_hi:[1,0]
	v_pk_mul_f32 v[142:143], v[74:75], v[194:195] op_sel_hi:[1,0]
	v_pk_fma_f32 v[140:141], v[180:181], v[140:141], v[164:165]
	v_pk_fma_f32 v[142:143], v[182:183], v[142:143], v[166:167]
	v_cvt_pk_bf16_f32 v140, v140, v141
	v_cvt_pk_bf16_f32 v141, v142, v143
	global_store_dwordx2 v224, v[140:141], s[100:101] offset:256
	v_pk_mul_f32 v[144:145], v[68:69], v[194:195] op_sel_hi:[1,0]
	v_pk_mul_f32 v[146:147], v[70:71], v[194:195] op_sel_hi:[1,0]
	v_pk_fma_f32 v[144:145], v[184:185], v[144:145], v[168:169]
	v_pk_fma_f32 v[146:147], v[186:187], v[146:147], v[170:171]
	v_cvt_pk_bf16_f32 v144, v144, v145
	v_cvt_pk_bf16_f32 v145, v146, v147
	global_store_dwordx2 v224, v[144:145], s[100:101] offset:288
	v_add_u32_e32 v224, 0x28000, v224
	global_store_dwordx4 v225, v[64:67], s[16:17]
	global_store_dwordx4 v225, v[60:63], s[16:17] offset:64
	global_store_dwordx4 v225, v[56:59], s[16:17] offset:512
	global_store_dwordx4 v225, v[52:55], s[16:17] offset:576
	v_add_u32_e32 v225, 0x10000, v225
	v_pk_mul_f32 v[132:133], v[64:65], v[196:197] op_sel_hi:[1,0]
	v_pk_mul_f32 v[134:135], v[66:67], v[196:197] op_sel_hi:[1,0]
	v_pk_fma_f32 v[132:133], v[172:173], v[132:133], v[156:157]
	v_pk_fma_f32 v[134:135], v[174:175], v[134:135], v[158:159]
	v_cvt_pk_bf16_f32 v132, v132, v133
	v_cvt_pk_bf16_f32 v133, v134, v135
	global_store_dwordx2 v224, v[132:133], s[100:101]
	v_pk_mul_f32 v[136:137], v[60:61], v[196:197] op_sel_hi:[1,0]
	v_pk_mul_f32 v[138:139], v[62:63], v[196:197] op_sel_hi:[1,0]
	v_pk_fma_f32 v[136:137], v[176:177], v[136:137], v[160:161]
	v_pk_fma_f32 v[138:139], v[178:179], v[138:139], v[162:163]
	v_cvt_pk_bf16_f32 v136, v136, v137
	v_cvt_pk_bf16_f32 v137, v138, v139
	global_store_dwordx2 v224, v[136:137], s[100:101] offset:32
	v_pk_mul_f32 v[140:141], v[56:57], v[196:197] op_sel_hi:[1,0]
	v_pk_mul_f32 v[142:143], v[58:59], v[196:197] op_sel_hi:[1,0]
	v_pk_fma_f32 v[140:141], v[180:181], v[140:141], v[164:165]
	v_pk_fma_f32 v[142:143], v[182:183], v[142:143], v[166:167]
	v_cvt_pk_bf16_f32 v140, v140, v141
	v_cvt_pk_bf16_f32 v141, v142, v143
	global_store_dwordx2 v224, v[140:141], s[100:101] offset:256
	v_pk_mul_f32 v[144:145], v[52:53], v[196:197] op_sel_hi:[1,0]
	v_pk_mul_f32 v[146:147], v[54:55], v[196:197] op_sel_hi:[1,0]
	v_pk_fma_f32 v[144:145], v[184:185], v[144:145], v[168:169]
	v_pk_fma_f32 v[146:147], v[186:187], v[146:147], v[170:171]
	v_cvt_pk_bf16_f32 v144, v144, v145
	v_cvt_pk_bf16_f32 v145, v146, v147
	global_store_dwordx2 v224, v[144:145], s[100:101] offset:288
	v_add_u32_e32 v224, 0x8000, v224
	global_store_dwordx4 v225, v[48:51], s[16:17]
	global_store_dwordx4 v225, v[44:47], s[16:17] offset:64
	global_store_dwordx4 v225, v[40:43], s[16:17] offset:512
	global_store_dwordx4 v225, v[36:39], s[16:17] offset:576
	v_add_u32_e32 v225, 0x10000, v225
	v_pk_mul_f32 v[132:133], v[48:49], v[198:199] op_sel_hi:[1,0]
	v_pk_mul_f32 v[134:135], v[50:51], v[198:199] op_sel_hi:[1,0]
	v_pk_fma_f32 v[132:133], v[172:173], v[132:133], v[156:157]
	v_pk_fma_f32 v[134:135], v[174:175], v[134:135], v[158:159]
	v_cvt_pk_bf16_f32 v132, v132, v133
	v_cvt_pk_bf16_f32 v133, v134, v135
	global_store_dwordx2 v224, v[132:133], s[100:101]
	v_pk_mul_f32 v[136:137], v[44:45], v[198:199] op_sel_hi:[1,0]
	v_pk_mul_f32 v[138:139], v[46:47], v[198:199] op_sel_hi:[1,0]
	v_pk_fma_f32 v[136:137], v[176:177], v[136:137], v[160:161]
	v_pk_fma_f32 v[138:139], v[178:179], v[138:139], v[162:163]
	v_cvt_pk_bf16_f32 v136, v136, v137
	v_cvt_pk_bf16_f32 v137, v138, v139
	global_store_dwordx2 v224, v[136:137], s[100:101] offset:32
	v_pk_mul_f32 v[140:141], v[40:41], v[198:199] op_sel_hi:[1,0]
	v_pk_mul_f32 v[142:143], v[42:43], v[198:199] op_sel_hi:[1,0]
	v_pk_fma_f32 v[140:141], v[180:181], v[140:141], v[164:165]
	v_pk_fma_f32 v[142:143], v[182:183], v[142:143], v[166:167]
	v_cvt_pk_bf16_f32 v140, v140, v141
	v_cvt_pk_bf16_f32 v141, v142, v143
	global_store_dwordx2 v224, v[140:141], s[100:101] offset:256
	v_pk_mul_f32 v[144:145], v[36:37], v[198:199] op_sel_hi:[1,0]
	v_pk_mul_f32 v[146:147], v[38:39], v[198:199] op_sel_hi:[1,0]
	v_pk_fma_f32 v[144:145], v[184:185], v[144:145], v[168:169]
	v_pk_fma_f32 v[146:147], v[186:187], v[146:147], v[170:171]
	v_cvt_pk_bf16_f32 v144, v144, v145
	v_cvt_pk_bf16_f32 v145, v146, v147
	global_store_dwordx2 v224, v[144:145], s[100:101] offset:288
	v_add_u32_e32 v224, 0x8000, v224
	global_store_dwordx4 v225, v[32:35], s[16:17]
	global_store_dwordx4 v225, v[28:31], s[16:17] offset:64
	global_store_dwordx4 v225, v[24:27], s[16:17] offset:512
	global_store_dwordx4 v225, v[20:23], s[16:17] offset:576
	v_add_u32_e32 v225, 0x10000, v225
	v_pk_mul_f32 v[132:133], v[32:33], v[200:201] op_sel_hi:[1,0]
	v_pk_mul_f32 v[134:135], v[34:35], v[200:201] op_sel_hi:[1,0]
	v_pk_fma_f32 v[132:133], v[172:173], v[132:133], v[156:157]
	v_pk_fma_f32 v[134:135], v[174:175], v[134:135], v[158:159]
	v_cvt_pk_bf16_f32 v132, v132, v133
	v_cvt_pk_bf16_f32 v133, v134, v135
	global_store_dwordx2 v224, v[132:133], s[100:101]
	v_pk_mul_f32 v[136:137], v[28:29], v[200:201] op_sel_hi:[1,0]
	v_pk_mul_f32 v[138:139], v[30:31], v[200:201] op_sel_hi:[1,0]
	v_pk_fma_f32 v[136:137], v[176:177], v[136:137], v[160:161]
	v_pk_fma_f32 v[138:139], v[178:179], v[138:139], v[162:163]
	v_cvt_pk_bf16_f32 v136, v136, v137
	v_cvt_pk_bf16_f32 v137, v138, v139
	global_store_dwordx2 v224, v[136:137], s[100:101] offset:32
	v_pk_mul_f32 v[140:141], v[24:25], v[200:201] op_sel_hi:[1,0]
	v_pk_mul_f32 v[142:143], v[26:27], v[200:201] op_sel_hi:[1,0]
	v_pk_fma_f32 v[140:141], v[180:181], v[140:141], v[164:165]
	v_pk_fma_f32 v[142:143], v[182:183], v[142:143], v[166:167]
	v_cvt_pk_bf16_f32 v140, v140, v141
	v_cvt_pk_bf16_f32 v141, v142, v143
	global_store_dwordx2 v224, v[140:141], s[100:101] offset:256
	v_pk_mul_f32 v[144:145], v[20:21], v[200:201] op_sel_hi:[1,0]
	v_pk_mul_f32 v[146:147], v[22:23], v[200:201] op_sel_hi:[1,0]
	v_pk_fma_f32 v[144:145], v[184:185], v[144:145], v[168:169]
	v_pk_fma_f32 v[146:147], v[186:187], v[146:147], v[170:171]
	v_cvt_pk_bf16_f32 v144, v144, v145
	v_cvt_pk_bf16_f32 v145, v146, v147
	global_store_dwordx2 v224, v[144:145], s[100:101] offset:288
	v_add_u32_e32 v224, 0x8000, v224
	global_store_dwordx4 v225, v[16:19], s[16:17]
	global_store_dwordx4 v225, v[8:11], s[16:17] offset:64
	global_store_dwordx4 v225, v[4:7], s[16:17] offset:512
	global_store_dwordx4 v225, v[0:3], s[16:17] offset:576
	v_pk_mul_f32 v[132:133], v[16:17], v[202:203] op_sel_hi:[1,0]
	v_pk_mul_f32 v[134:135], v[18:19], v[202:203] op_sel_hi:[1,0]
	v_pk_fma_f32 v[132:133], v[172:173], v[132:133], v[156:157]
	v_pk_fma_f32 v[134:135], v[174:175], v[134:135], v[158:159]
	v_cvt_pk_bf16_f32 v132, v132, v133
	v_cvt_pk_bf16_f32 v133, v134, v135
	global_store_dwordx2 v224, v[132:133], s[100:101]
	v_pk_mul_f32 v[136:137], v[8:9], v[202:203] op_sel_hi:[1,0]
	v_pk_mul_f32 v[138:139], v[10:11], v[202:203] op_sel_hi:[1,0]
	v_pk_fma_f32 v[136:137], v[176:177], v[136:137], v[160:161]
	v_pk_fma_f32 v[138:139], v[178:179], v[138:139], v[162:163]
	v_cvt_pk_bf16_f32 v136, v136, v137
	v_cvt_pk_bf16_f32 v137, v138, v139
	global_store_dwordx2 v224, v[136:137], s[100:101] offset:32
	v_pk_mul_f32 v[140:141], v[4:5], v[202:203] op_sel_hi:[1,0]
	v_pk_mul_f32 v[142:143], v[6:7], v[202:203] op_sel_hi:[1,0]
	v_pk_fma_f32 v[140:141], v[180:181], v[140:141], v[164:165]
	v_pk_fma_f32 v[142:143], v[182:183], v[142:143], v[166:167]
	v_cvt_pk_bf16_f32 v140, v140, v141
	v_cvt_pk_bf16_f32 v141, v142, v143
	global_store_dwordx2 v224, v[140:141], s[100:101] offset:256
	v_pk_mul_f32 v[144:145], v[0:1], v[202:203] op_sel_hi:[1,0]
	v_pk_mul_f32 v[146:147], v[2:3], v[202:203] op_sel_hi:[1,0]
	v_pk_fma_f32 v[144:145], v[184:185], v[144:145], v[168:169]
	v_pk_fma_f32 v[146:147], v[186:187], v[146:147], v[170:171]
	v_cvt_pk_bf16_f32 v144, v144, v145
	v_cvt_pk_bf16_f32 v145, v146, v147
	global_store_dwordx2 v224, v[144:145], s[100:101] offset:288
	s_branch .LBB0_400

.LBB0_498:
	s_or_b64 s[16:17], s[6:7], s[16:17]
	s_and_b64 vcc, exec, s[16:17]
	s_cbranch_vccnz .LBB0_500
	s_lshl_b64 s[14:15], s[14:15], 10
	v_lshl_add_u64 v[44:45], s[14:15], 1, v[38:39]
	s_waitcnt lgkmcnt(0)
	global_load_dwordx2 v[64:65], v[44:45], off
	global_load_dwordx2 v[66:67], v[44:45], off offset:512
	global_load_dwordx2 v[68:69], v[44:45], off offset:1024
	global_load_dwordx2 v[70:71], v[44:45], off offset:1536
	v_add_co_u32_e32 v46, vcc, 0x400000, v44
	s_nop 1
	v_addc_co_u32_e32 v47, vcc, 0, v45, vcc
	global_load_dwordx2 v[72:73], v[46:47], off
	global_load_dwordx2 v[74:75], v[46:47], off offset:512
	global_load_dwordx2 v[76:77], v[46:47], off offset:1024
	global_load_dwordx2 v[78:79], v[46:47], off offset:1536
	v_add_co_u32_e32 v46, vcc, 0x800000, v44
	s_nop 1
	v_addc_co_u32_e32 v47, vcc, 0, v45, vcc
	global_load_dwordx2 v[80:81], v[46:47], off
	global_load_dwordx2 v[82:83], v[46:47], off offset:512
	global_load_dwordx2 v[84:85], v[46:47], off offset:1024
	global_load_dwordx2 v[86:87], v[46:47], off offset:1536
	v_add_co_u32_e32 v46, vcc, 0xc00000, v44
	s_nop 1
	v_addc_co_u32_e32 v47, vcc, 0, v45, vcc
	global_load_dwordx2 v[88:89], v[46:47], off
	global_load_dwordx2 v[90:91], v[46:47], off offset:512
	global_load_dwordx2 v[92:93], v[46:47], off offset:1024
	global_load_dwordx2 v[94:95], v[46:47], off offset:1536
	v_add_co_u32_e32 v46, vcc, 0x1000000, v44
	s_nop 1
	v_addc_co_u32_e32 v47, vcc, 0, v45, vcc
	global_load_dwordx2 v[96:97], v[46:47], off
	global_load_dwordx2 v[98:99], v[46:47], off offset:512
	global_load_dwordx2 v[100:101], v[46:47], off offset:1024
	global_load_dwordx2 v[102:103], v[46:47], off offset:1536
	v_add_co_u32_e32 v46, vcc, 0x1400000, v44
	s_nop 1
	v_addc_co_u32_e32 v47, vcc, 0, v45, vcc
	global_load_dwordx2 v[104:105], v[46:47], off
	global_load_dwordx2 v[106:107], v[46:47], off offset:512
	global_load_dwordx2 v[108:109], v[46:47], off offset:1024
	global_load_dwordx2 v[110:111], v[46:47], off offset:1536
	v_add_co_u32_e32 v46, vcc, 0x1800000, v44
	s_nop 1
	v_addc_co_u32_e32 v47, vcc, 0, v45, vcc
	global_load_dwordx2 v[112:113], v[46:47], off
	global_load_dwordx2 v[114:115], v[46:47], off offset:512
	global_load_dwordx2 v[116:117], v[46:47], off offset:1024
	global_load_dwordx2 v[118:119], v[46:47], off offset:1536
	v_add_co_u32_e32 v46, vcc, 0x1c00000, v44
	s_nop 1
	v_addc_co_u32_e32 v47, vcc, 0, v45, vcc
	global_load_dwordx2 v[120:121], v[46:47], off
	global_load_dwordx2 v[122:123], v[46:47], off offset:512
	global_load_dwordx2 v[124:125], v[46:47], off offset:1024
	global_load_dwordx2 v[126:127], v[46:47], off offset:1536
	s_waitcnt vmcnt(28)
	v_lshlrev_b32_e32 v54, 16, v64
	v_and_b32_e32 v55, 0xffff0000, v64
	v_lshlrev_b32_e32 v56, 16, v65
	v_and_b32_e32 v57, 0xffff0000, v65
	v_pk_add_f32 v[26:27], v[26:27], v[54:55]
	v_pk_add_f32 v[28:29], v[28:29], v[56:57]
	v_lshlrev_b32_e32 v54, 16, v66
	v_and_b32_e32 v55, 0xffff0000, v66
	v_lshlrev_b32_e32 v56, 16, v67
	v_and_b32_e32 v57, 0xffff0000, v67
	v_pk_add_f32 v[22:23], v[22:23], v[54:55]
	v_pk_add_f32 v[24:25], v[24:25], v[56:57]
	v_lshlrev_b32_e32 v54, 16, v68
	v_and_b32_e32 v55, 0xffff0000, v68
	v_lshlrev_b32_e32 v56, 16, v69
	v_and_b32_e32 v57, 0xffff0000, v69
	v_pk_add_f32 v[18:19], v[18:19], v[54:55]
	v_pk_add_f32 v[20:21], v[20:21], v[56:57]
	v_lshlrev_b32_e32 v54, 16, v70
	v_and_b32_e32 v55, 0xffff0000, v70
	v_lshlrev_b32_e32 v56, 16, v71
	v_and_b32_e32 v57, 0xffff0000, v71
	v_pk_add_f32 v[30:31], v[30:31], v[54:55]
	v_pk_add_f32 v[32:33], v[32:33], v[56:57]
	s_waitcnt vmcnt(24)
	v_lshlrev_b32_e32 v54, 16, v72
	v_and_b32_e32 v55, 0xffff0000, v72
	v_lshlrev_b32_e32 v56, 16, v73
	v_and_b32_e32 v57, 0xffff0000, v73
	v_pk_add_f32 v[26:27], v[26:27], v[54:55]
	v_pk_add_f32 v[28:29], v[28:29], v[56:57]
	v_lshlrev_b32_e32 v54, 16, v74
	v_and_b32_e32 v55, 0xffff0000, v74
	v_lshlrev_b32_e32 v56, 16, v75
	v_and_b32_e32 v57, 0xffff0000, v75
	v_pk_add_f32 v[22:23], v[22:23], v[54:55]
	v_pk_add_f32 v[24:25], v[24:25], v[56:57]
	v_lshlrev_b32_e32 v54, 16, v76
	v_and_b32_e32 v55, 0xffff0000, v76
	v_lshlrev_b32_e32 v56, 16, v77
	v_and_b32_e32 v57, 0xffff0000, v77
	v_pk_add_f32 v[18:19], v[18:19], v[54:55]
	v_pk_add_f32 v[20:21], v[20:21], v[56:57]
	v_lshlrev_b32_e32 v54, 16, v78
	v_and_b32_e32 v55, 0xffff0000, v78
	v_lshlrev_b32_e32 v56, 16, v79
	v_and_b32_e32 v57, 0xffff0000, v79
	v_pk_add_f32 v[30:31], v[30:31], v[54:55]
	v_pk_add_f32 v[32:33], v[32:33], v[56:57]
	s_waitcnt vmcnt(20)
	v_lshlrev_b32_e32 v54, 16, v80
	v_and_b32_e32 v55, 0xffff0000, v80
	v_lshlrev_b32_e32 v56, 16, v81
	v_and_b32_e32 v57, 0xffff0000, v81
	v_pk_add_f32 v[26:27], v[26:27], v[54:55]
	v_pk_add_f32 v[28:29], v[28:29], v[56:57]
	v_lshlrev_b32_e32 v54, 16, v82
	v_and_b32_e32 v55, 0xffff0000, v82
	v_lshlrev_b32_e32 v56, 16, v83
	v_and_b32_e32 v57, 0xffff0000, v83
	v_pk_add_f32 v[22:23], v[22:23], v[54:55]
	v_pk_add_f32 v[24:25], v[24:25], v[56:57]
	v_lshlrev_b32_e32 v54, 16, v84
	v_and_b32_e32 v55, 0xffff0000, v84
	v_lshlrev_b32_e32 v56, 16, v85
	v_and_b32_e32 v57, 0xffff0000, v85
	v_pk_add_f32 v[18:19], v[18:19], v[54:55]
	v_pk_add_f32 v[20:21], v[20:21], v[56:57]
	v_lshlrev_b32_e32 v54, 16, v86
	v_and_b32_e32 v55, 0xffff0000, v86
	v_lshlrev_b32_e32 v56, 16, v87
	v_and_b32_e32 v57, 0xffff0000, v87
	v_pk_add_f32 v[30:31], v[30:31], v[54:55]
	v_pk_add_f32 v[32:33], v[32:33], v[56:57]
	s_waitcnt vmcnt(16)
	v_lshlrev_b32_e32 v54, 16, v88
	v_and_b32_e32 v55, 0xffff0000, v88
	v_lshlrev_b32_e32 v56, 16, v89
	v_and_b32_e32 v57, 0xffff0000, v89
	v_pk_add_f32 v[26:27], v[26:27], v[54:55]
	v_pk_add_f32 v[28:29], v[28:29], v[56:57]
	v_lshlrev_b32_e32 v54, 16, v90
	v_and_b32_e32 v55, 0xffff0000, v90
	v_lshlrev_b32_e32 v56, 16, v91
	v_and_b32_e32 v57, 0xffff0000, v91
	v_pk_add_f32 v[22:23], v[22:23], v[54:55]
	v_pk_add_f32 v[24:25], v[24:25], v[56:57]
	v_lshlrev_b32_e32 v54, 16, v92
	v_and_b32_e32 v55, 0xffff0000, v92
	v_lshlrev_b32_e32 v56, 16, v93
	v_and_b32_e32 v57, 0xffff0000, v93
	v_pk_add_f32 v[18:19], v[18:19], v[54:55]
	v_pk_add_f32 v[20:21], v[20:21], v[56:57]
	v_lshlrev_b32_e32 v54, 16, v94
	v_and_b32_e32 v55, 0xffff0000, v94
	v_lshlrev_b32_e32 v56, 16, v95
	v_and_b32_e32 v57, 0xffff0000, v95
	v_pk_add_f32 v[30:31], v[30:31], v[54:55]
	v_pk_add_f32 v[32:33], v[32:33], v[56:57]
	s_waitcnt vmcnt(12)
	v_lshlrev_b32_e32 v54, 16, v96
	v_and_b32_e32 v55, 0xffff0000, v96
	v_lshlrev_b32_e32 v56, 16, v97
	v_and_b32_e32 v57, 0xffff0000, v97
	v_pk_add_f32 v[26:27], v[26:27], v[54:55]
	v_pk_add_f32 v[28:29], v[28:29], v[56:57]
	v_lshlrev_b32_e32 v54, 16, v98
	v_and_b32_e32 v55, 0xffff0000, v98
	v_lshlrev_b32_e32 v56, 16, v99
	v_and_b32_e32 v57, 0xffff0000, v99
	v_pk_add_f32 v[22:23], v[22:23], v[54:55]
	v_pk_add_f32 v[24:25], v[24:25], v[56:57]
	v_lshlrev_b32_e32 v54, 16, v100
	v_and_b32_e32 v55, 0xffff0000, v100
	v_lshlrev_b32_e32 v56, 16, v101
	v_and_b32_e32 v57, 0xffff0000, v101
	v_pk_add_f32 v[18:19], v[18:19], v[54:55]
	v_pk_add_f32 v[20:21], v[20:21], v[56:57]
	v_lshlrev_b32_e32 v54, 16, v102
	v_and_b32_e32 v55, 0xffff0000, v102
	v_lshlrev_b32_e32 v56, 16, v103
	v_and_b32_e32 v57, 0xffff0000, v103
	v_pk_add_f32 v[30:31], v[30:31], v[54:55]
	v_pk_add_f32 v[32:33], v[32:33], v[56:57]
	s_waitcnt vmcnt(8)
	v_lshlrev_b32_e32 v54, 16, v104
	v_and_b32_e32 v55, 0xffff0000, v104
	v_lshlrev_b32_e32 v56, 16, v105
	v_and_b32_e32 v57, 0xffff0000, v105
	v_pk_add_f32 v[26:27], v[26:27], v[54:55]
	v_pk_add_f32 v[28:29], v[28:29], v[56:57]
	v_lshlrev_b32_e32 v54, 16, v106
	v_and_b32_e32 v55, 0xffff0000, v106
	v_lshlrev_b32_e32 v56, 16, v107
	v_and_b32_e32 v57, 0xffff0000, v107
	v_pk_add_f32 v[22:23], v[22:23], v[54:55]
	v_pk_add_f32 v[24:25], v[24:25], v[56:57]
	v_lshlrev_b32_e32 v54, 16, v108
	v_and_b32_e32 v55, 0xffff0000, v108
	v_lshlrev_b32_e32 v56, 16, v109
	v_and_b32_e32 v57, 0xffff0000, v109
	v_pk_add_f32 v[18:19], v[18:19], v[54:55]
	v_pk_add_f32 v[20:21], v[20:21], v[56:57]
	v_lshlrev_b32_e32 v54, 16, v110
	v_and_b32_e32 v55, 0xffff0000, v110
	v_lshlrev_b32_e32 v56, 16, v111
	v_and_b32_e32 v57, 0xffff0000, v111
	v_pk_add_f32 v[30:31], v[30:31], v[54:55]
	v_pk_add_f32 v[32:33], v[32:33], v[56:57]
	s_waitcnt vmcnt(4)
	v_lshlrev_b32_e32 v54, 16, v112
	v_and_b32_e32 v55, 0xffff0000, v112
	v_lshlrev_b32_e32 v56, 16, v113
	v_and_b32_e32 v57, 0xffff0000, v113
	v_pk_add_f32 v[26:27], v[26:27], v[54:55]
	v_pk_add_f32 v[28:29], v[28:29], v[56:57]
	v_lshlrev_b32_e32 v54, 16, v114
	v_and_b32_e32 v55, 0xffff0000, v114
	v_lshlrev_b32_e32 v56, 16, v115
	v_and_b32_e32 v57, 0xffff0000, v115
	v_pk_add_f32 v[22:23], v[22:23], v[54:55]
	v_pk_add_f32 v[24:25], v[24:25], v[56:57]
	v_lshlrev_b32_e32 v54, 16, v116
	v_and_b32_e32 v55, 0xffff0000, v116
	v_lshlrev_b32_e32 v56, 16, v117
	v_and_b32_e32 v57, 0xffff0000, v117
	v_pk_add_f32 v[18:19], v[18:19], v[54:55]
	v_pk_add_f32 v[20:21], v[20:21], v[56:57]
	v_lshlrev_b32_e32 v54, 16, v118
	v_and_b32_e32 v55, 0xffff0000, v118
	v_lshlrev_b32_e32 v56, 16, v119
	v_and_b32_e32 v57, 0xffff0000, v119
	v_pk_add_f32 v[30:31], v[30:31], v[54:55]
	v_pk_add_f32 v[32:33], v[32:33], v[56:57]
	s_waitcnt vmcnt(0)
	v_lshlrev_b32_e32 v54, 16, v120
	v_and_b32_e32 v55, 0xffff0000, v120
	v_lshlrev_b32_e32 v56, 16, v121
	v_and_b32_e32 v57, 0xffff0000, v121
	v_pk_add_f32 v[26:27], v[26:27], v[54:55]
	v_pk_add_f32 v[28:29], v[28:29], v[56:57]
	v_lshlrev_b32_e32 v54, 16, v122
	v_and_b32_e32 v55, 0xffff0000, v122
	v_lshlrev_b32_e32 v56, 16, v123
	v_and_b32_e32 v57, 0xffff0000, v123
	v_pk_add_f32 v[22:23], v[22:23], v[54:55]
	v_pk_add_f32 v[24:25], v[24:25], v[56:57]
	v_lshlrev_b32_e32 v54, 16, v124
	v_and_b32_e32 v55, 0xffff0000, v124
	v_lshlrev_b32_e32 v56, 16, v125
	v_and_b32_e32 v57, 0xffff0000, v125
	v_pk_add_f32 v[18:19], v[18:19], v[54:55]
	v_pk_add_f32 v[20:21], v[20:21], v[56:57]
	v_lshlrev_b32_e32 v54, 16, v126
	v_and_b32_e32 v55, 0xffff0000, v126
	v_lshlrev_b32_e32 v56, 16, v127
	v_and_b32_e32 v57, 0xffff0000, v127
	v_pk_add_f32 v[30:31], v[30:31], v[54:55]
	v_pk_add_f32 v[32:33], v[32:33], v[56:57]
	v_lshl_add_u64 v[44:45], s[14:15], 2, v[40:41]
	global_store_dwordx4 v[44:45], v[26:29], off
	global_store_dwordx4 v[44:45], v[22:25], off offset:1024
	global_store_dwordx4 v[44:45], v[18:21], off offset:2048
	global_store_dwordx4 v[44:45], v[30:33], off offset:3072

.LBB0_957:
	s_or_b64 exec, exec, s[16:17]
	s_lshr_b32 s100, s10, 3
	s_mul_i32 s100, s100, 0x9000
	v_add_u32_e32 v225, 0x1000, v222
	s_add_u32 s100, s100, 0x46000
	s_add_u32 s100, s14, s100
	s_addc_u32 s101, s15, 0
	s_add_u32 s100, s18, s100
	s_addc_u32 s101, s19, s101
	global_load_dwordx4 v[156:159], v222, s[100:101]
	global_load_dwordx4 v[160:163], v222, s[100:101] offset:64
	global_load_dwordx4 v[164:167], v222, s[100:101] offset:512
	global_load_dwordx4 v[168:171], v222, s[100:101] offset:576
	global_load_dwordx4 v[172:175], v225, s[100:101]
	global_load_dwordx4 v[176:179], v225, s[100:101] offset:64
	global_load_dwordx4 v[180:183], v225, s[100:101] offset:512
	global_load_dwordx4 v[184:187], v225, s[100:101] offset:576
	s_cmp_gt_u32 s7, 63
	s_cbranch_scc1 .LBB0_967
	s_lshl_b32 s16, s10, 4
	s_ashr_i32 s17, s16, 31
	s_lshl_b64 s[16:17], s[16:17], 2
	s_add_u32 s16, s9, s16
	s_addc_u32 s17, s11, s17
	s_mov_b32 s7, 0x400001
	s_branch .LBB0_960

.LBB0_969:
	s_or_b64 exec, exec, s[16:17]
	s_waitcnt vmcnt(0) lgkmcnt(0)
	s_barrier
	ds_read_b32 v188, v221 offset:16384
	ds_read_b32 v190, v221 offset:16448
	ds_read_b32 v192, v221 offset:16512
	ds_read_b32 v194, v221 offset:16576
	ds_read_b32 v196, v221 offset:16896
	ds_read_b32 v198, v221 offset:16960
	ds_read_b32 v200, v221 offset:17024
	ds_read_b32 v202, v221 offset:17088
	s_add_u32 s100, s12, 0x3100000
	s_addc_u32 s101, s13, 0
	v_lshrrev_b32_e32 v224, 1, v220
	v_pk_add_f32 v[172:173], v[172:173], 1.0 op_sel_hi:[1,0]
	v_pk_add_f32 v[174:175], v[174:175], 1.0 op_sel_hi:[1,0]
	v_pk_add_f32 v[176:177], v[176:177], 1.0 op_sel_hi:[1,0]
	v_pk_add_f32 v[178:179], v[178:179], 1.0 op_sel_hi:[1,0]
	v_pk_add_f32 v[180:181], v[180:181], 1.0 op_sel_hi:[1,0]
	v_pk_add_f32 v[182:183], v[182:183], 1.0 op_sel_hi:[1,0]
	v_pk_add_f32 v[184:185], v[184:185], 1.0 op_sel_hi:[1,0]
	v_pk_add_f32 v[186:187], v[186:187], 1.0 op_sel_hi:[1,0]
	s_waitcnt lgkmcnt(0)
	v_mov_b32_e32 v225, v220
	global_store_dwordx4 v225, v[128:131], s[4:5]
	global_store_dwordx4 v225, v[124:127], s[4:5] offset:64
	global_store_dwordx4 v225, v[120:123], s[4:5] offset:512
	global_store_dwordx4 v225, v[116:119], s[4:5] offset:576
	v_add_u32_e32 v225, 0x10000, v225
	v_pk_mul_f32 v[132:133], v[128:129], v[188:189] op_sel_hi:[1,0]
	v_pk_mul_f32 v[134:135], v[130:131], v[188:189] op_sel_hi:[1,0]
	v_pk_fma_f32 v[132:133], v[172:173], v[132:133], v[156:157]
	v_pk_fma_f32 v[134:135], v[174:175], v[134:135], v[158:159]
	v_cvt_pk_bf16_f32 v132, v132, v133
	v_cvt_pk_bf16_f32 v133, v134, v135
	global_store_dwordx2 v224, v[132:133], s[100:101]
	v_pk_mul_f32 v[136:137], v[124:125], v[188:189] op_sel_hi:[1,0]
	v_pk_mul_f32 v[138:139], v[126:127], v[188:189] op_sel_hi:[1,0]
	v_pk_fma_f32 v[136:137], v[176:177], v[136:137], v[160:161]
	v_pk_fma_f32 v[138:139], v[178:179], v[138:139], v[162:163]
	v_cvt_pk_bf16_f32 v136, v136, v137
	v_cvt_pk_bf16_f32 v137, v138, v139
	global_store_dwordx2 v224, v[136:137], s[100:101] offset:32
	v_pk_mul_f32 v[140:141], v[120:121], v[188:189] op_sel_hi:[1,0]
	v_pk_mul_f32 v[142:143], v[122:123], v[188:189] op_sel_hi:[1,0]
	v_pk_fma_f32 v[140:141], v[180:181], v[140:141], v[164:165]
	v_pk_fma_f32 v[142:143], v[182:183], v[142:143], v[166:167]
	v_cvt_pk_bf16_f32 v140, v140, v141
	v_cvt_pk_bf16_f32 v141, v142, v143
	global_store_dwordx2 v224, v[140:141], s[100:101] offset:256
	v_pk_mul_f32 v[144:145], v[116:117], v[188:189] op_sel_hi:[1,0]
	v_pk_mul_f32 v[146:147], v[118:119], v[188:189] op_sel_hi:[1,0]
	v_pk_fma_f32 v[144:145], v[184:185], v[144:145], v[168:169]
	v_pk_fma_f32 v[146:147], v[186:187], v[146:147], v[170:171]
	v_cvt_pk_bf16_f32 v144, v144, v145
	v_cvt_pk_bf16_f32 v145, v146, v147
	global_store_dwordx2 v224, v[144:145], s[100:101] offset:288
	v_add_u32_e32 v224, 0x8000, v224
	global_store_dwordx4 v225, v[112:115], s[4:5]
	global_store_dwordx4 v225, v[108:111], s[4:5] offset:64
	global_store_dwordx4 v225, v[104:107], s[4:5] offset:512
	global_store_dwordx4 v225, v[100:103], s[4:5] offset:576
	v_add_u32_e32 v225, 0x10000, v225
	v_pk_mul_f32 v[132:133], v[112:113], v[190:191] op_sel_hi:[1,0]
	v_pk_mul_f32 v[134:135], v[114:115], v[190:191] op_sel_hi:[1,0]
	v_pk_fma_f32 v[132:133], v[172:173], v[132:133], v[156:157]
	v_pk_fma_f32 v[134:135], v[174:175], v[134:135], v[158:159]
	v_cvt_pk_bf16_f32 v132, v132, v133
	v_cvt_pk_bf16_f32 v133, v134, v135
	global_store_dwordx2 v224, v[132:133], s[100:101]
	v_pk_mul_f32 v[136:137], v[108:109], v[190:191] op_sel_hi:[1,0]
	v_pk_mul_f32 v[138:139], v[110:111], v[190:191] op_sel_hi:[1,0]
	v_pk_fma_f32 v[136:137], v[176:177], v[136:137], v[160:161]
	v_pk_fma_f32 v[138:139], v[178:179], v[138:139], v[162:163]
	v_cvt_pk_bf16_f32 v136, v136, v137
	v_cvt_pk_bf16_f32 v137, v138, v139
	global_store_dwordx2 v224, v[136:137], s[100:101] offset:32
	v_pk_mul_f32 v[140:141], v[104:105], v[190:191] op_sel_hi:[1,0]
	v_pk_mul_f32 v[142:143], v[106:107], v[190:191] op_sel_hi:[1,0]
	v_pk_fma_f32 v[140:141], v[180:181], v[140:141], v[164:165]
	v_pk_fma_f32 v[142:143], v[182:183], v[142:143], v[166:167]
	v_cvt_pk_bf16_f32 v140, v140, v141
	v_cvt_pk_bf16_f32 v141, v142, v143
	global_store_dwordx2 v224, v[140:141], s[100:101] offset:256
	v_pk_mul_f32 v[144:145], v[100:101], v[190:191] op_sel_hi:[1,0]
	v_pk_mul_f32 v[146:147], v[102:103], v[190:191] op_sel_hi:[1,0]
	v_pk_fma_f32 v[144:145], v[184:185], v[144:145], v[168:169]
	v_pk_fma_f32 v[146:147], v[186:187], v[146:147], v[170:171]
	v_cvt_pk_bf16_f32 v144, v144, v145
	v_cvt_pk_bf16_f32 v145, v146, v147
	global_store_dwordx2 v224, v[144:145], s[100:101] offset:288
	v_add_u32_e32 v224, 0x8000, v224
	global_store_dwordx4 v225, v[96:99], s[4:5]
	global_store_dwordx4 v225, v[92:95], s[4:5] offset:64
	global_store_dwordx4 v225, v[88:91], s[4:5] offset:512
	global_store_dwordx4 v225, v[84:87], s[4:5] offset:576
	v_add_u32_e32 v225, 0x10000, v225
	v_pk_mul_f32 v[132:133], v[96:97], v[192:193] op_sel_hi:[1,0]
	v_pk_mul_f32 v[134:135], v[98:99], v[192:193] op_sel_hi:[1,0]
	v_pk_fma_f32 v[132:133], v[172:173], v[132:133], v[156:157]
	v_pk_fma_f32 v[134:135], v[174:175], v[134:135], v[158:159]
	v_cvt_pk_bf16_f32 v132, v132, v133
	v_cvt_pk_bf16_f32 v133, v134, v135
	global_store_dwordx2 v224, v[132:133], s[100:101]
	v_pk_mul_f32 v[136:137], v[92:93], v[192:193] op_sel_hi:[1,0]
	v_pk_mul_f32 v[138:139], v[94:95], v[192:193] op_sel_hi:[1,0]
	v_pk_fma_f32 v[136:137], v[176:177], v[136:137], v[160:161]
	v_pk_fma_f32 v[138:139], v[178:179], v[138:139], v[162:163]
	v_cvt_pk_bf16_f32 v136, v136, v137
	v_cvt_pk_bf16_f32 v137, v138, v139
	global_store_dwordx2 v224, v[136:137], s[100:101] offset:32
	v_pk_mul_f32 v[140:141], v[88:89], v[192:193] op_sel_hi:[1,0]
	v_pk_mul_f32 v[142:143], v[90:91], v[192:193] op_sel_hi:[1,0]
	v_pk_fma_f32 v[140:141], v[180:181], v[140:141], v[164:165]
	v_pk_fma_f32 v[142:143], v[182:183], v[142:143], v[166:167]
	v_cvt_pk_bf16_f32 v140, v140, v141
	v_cvt_pk_bf16_f32 v141, v142, v143
	global_store_dwordx2 v224, v[140:141], s[100:101] offset:256
	v_pk_mul_f32 v[144:145], v[84:85], v[192:193] op_sel_hi:[1,0]
	v_pk_mul_f32 v[146:147], v[86:87], v[192:193] op_sel_hi:[1,0]
	v_pk_fma_f32 v[144:145], v[184:185], v[144:145], v[168:169]
	v_pk_fma_f32 v[146:147], v[186:187], v[146:147], v[170:171]
	v_cvt_pk_bf16_f32 v144, v144, v145
	v_cvt_pk_bf16_f32 v145, v146, v147
	global_store_dwordx2 v224, v[144:145], s[100:101] offset:288
	v_add_u32_e32 v224, 0x8000, v224
	global_store_dwordx4 v225, v[80:83], s[4:5]
	global_store_dwordx4 v225, v[76:79], s[4:5] offset:64
	global_store_dwordx4 v225, v[72:75], s[4:5] offset:512
	global_store_dwordx4 v225, v[68:71], s[4:5] offset:576
	v_add_u32_e32 v225, 0x50000, v225
	v_pk_mul_f32 v[132:133], v[80:81], v[194:195] op_sel_hi:[1,0]
	v_pk_mul_f32 v[134:135], v[82:83], v[194:195] op_sel_hi:[1,0]
	v_pk_fma_f32 v[132:133], v[172:173], v[132:133], v[156:157]
	v_pk_fma_f32 v[134:135], v[174:175], v[134:135], v[158:159]
	v_cvt_pk_bf16_f32 v132, v132, v133
	v_cvt_pk_bf16_f32 v133, v134, v135
	global_store_dwordx2 v224, v[132:133], s[100:101]
	v_pk_mul_f32 v[136:137], v[76:77], v[194:195] op_sel_hi:[1,0]
	v_pk_mul_f32 v[138:139], v[78:79], v[194:195] op_sel_hi:[1,0]
	v_pk_fma_f32 v[136:137], v[176:177], v[136:137], v[160:161]
	v_pk_fma_f32 v[138:139], v[178:179], v[138:139], v[162:163]
	v_cvt_pk_bf16_f32 v136, v136, v137
	v_cvt_pk_bf16_f32 v137, v138, v139
	global_store_dwordx2 v224, v[136:137], s[100:101] offset:32
	v_pk_mul_f32 v[140:141], v[72:73], v[194:195] op_sel_hi:[1,0]
	v_pk_mul_f32 v[142:143], v[74:75], v[194:195] op_sel_hi:[1,0]
	v_pk_fma_f32 v[140:141], v[180:181], v[140:141], v[164:165]
	v_pk_fma_f32 v[142:143], v[182:183], v[142:143], v[166:167]
	v_cvt_pk_bf16_f32 v140, v140, v141
	v_cvt_pk_bf16_f32 v141, v142, v143
	global_store_dwordx2 v224, v[140:141], s[100:101] offset:256
	v_pk_mul_f32 v[144:145], v[68:69], v[194:195] op_sel_hi:[1,0]
	v_pk_mul_f32 v[146:147], v[70:71], v[194:195] op_sel_hi:[1,0]
	v_pk_fma_f32 v[144:145], v[184:185], v[144:145], v[168:169]
	v_pk_fma_f32 v[146:147], v[186:187], v[146:147], v[170:171]
	v_cvt_pk_bf16_f32 v144, v144, v145
	v_cvt_pk_bf16_f32 v145, v146, v147
	global_store_dwordx2 v224, v[144:145], s[100:101] offset:288
	v_add_u32_e32 v224, 0x28000, v224
	global_store_dwordx4 v225, v[64:67], s[4:5]
	global_store_dwordx4 v225, v[60:63], s[4:5] offset:64
	global_store_dwordx4 v225, v[56:59], s[4:5] offset:512
	global_store_dwordx4 v225, v[52:55], s[4:5] offset:576
	v_add_u32_e32 v225, 0x10000, v225
	v_pk_mul_f32 v[132:133], v[64:65], v[196:197] op_sel_hi:[1,0]
	v_pk_mul_f32 v[134:135], v[66:67], v[196:197] op_sel_hi:[1,0]
	v_pk_fma_f32 v[132:133], v[172:173], v[132:133], v[156:157]
	v_pk_fma_f32 v[134:135], v[174:175], v[134:135], v[158:159]
	v_cvt_pk_bf16_f32 v132, v132, v133
	v_cvt_pk_bf16_f32 v133, v134, v135
	global_store_dwordx2 v224, v[132:133], s[100:101]
	v_pk_mul_f32 v[136:137], v[60:61], v[196:197] op_sel_hi:[1,0]
	v_pk_mul_f32 v[138:139], v[62:63], v[196:197] op_sel_hi:[1,0]
	v_pk_fma_f32 v[136:137], v[176:177], v[136:137], v[160:161]
	v_pk_fma_f32 v[138:139], v[178:179], v[138:139], v[162:163]
	v_cvt_pk_bf16_f32 v136, v136, v137
	v_cvt_pk_bf16_f32 v137, v138, v139
	global_store_dwordx2 v224, v[136:137], s[100:101] offset:32
	v_pk_mul_f32 v[140:141], v[56:57], v[196:197] op_sel_hi:[1,0]
	v_pk_mul_f32 v[142:143], v[58:59], v[196:197] op_sel_hi:[1,0]
	v_pk_fma_f32 v[140:141], v[180:181], v[140:141], v[164:165]
	v_pk_fma_f32 v[142:143], v[182:183], v[142:143], v[166:167]
	v_cvt_pk_bf16_f32 v140, v140, v141
	v_cvt_pk_bf16_f32 v141, v142, v143
	global_store_dwordx2 v224, v[140:141], s[100:101] offset:256
	v_pk_mul_f32 v[144:145], v[52:53], v[196:197] op_sel_hi:[1,0]
	v_pk_mul_f32 v[146:147], v[54:55], v[196:197] op_sel_hi:[1,0]
	v_pk_fma_f32 v[144:145], v[184:185], v[144:145], v[168:169]
	v_pk_fma_f32 v[146:147], v[186:187], v[146:147], v[170:171]
	v_cvt_pk_bf16_f32 v144, v144, v145
	v_cvt_pk_bf16_f32 v145, v146, v147
	global_store_dwordx2 v224, v[144:145], s[100:101] offset:288
	v_add_u32_e32 v224, 0x8000, v224
	global_store_dwordx4 v225, v[48:51], s[4:5]
	global_store_dwordx4 v225, v[44:47], s[4:5] offset:64
	global_store_dwordx4 v225, v[40:43], s[4:5] offset:512
	global_store_dwordx4 v225, v[36:39], s[4:5] offset:576
	v_add_u32_e32 v225, 0x10000, v225
	v_pk_mul_f32 v[132:133], v[48:49], v[198:199] op_sel_hi:[1,0]
	v_pk_mul_f32 v[134:135], v[50:51], v[198:199] op_sel_hi:[1,0]
	v_pk_fma_f32 v[132:133], v[172:173], v[132:133], v[156:157]
	v_pk_fma_f32 v[134:135], v[174:175], v[134:135], v[158:159]
	v_cvt_pk_bf16_f32 v132, v132, v133
	v_cvt_pk_bf16_f32 v133, v134, v135
	global_store_dwordx2 v224, v[132:133], s[100:101]
	v_pk_mul_f32 v[136:137], v[44:45], v[198:199] op_sel_hi:[1,0]
	v_pk_mul_f32 v[138:139], v[46:47], v[198:199] op_sel_hi:[1,0]
	v_pk_fma_f32 v[136:137], v[176:177], v[136:137], v[160:161]
	v_pk_fma_f32 v[138:139], v[178:179], v[138:139], v[162:163]
	v_cvt_pk_bf16_f32 v136, v136, v137
	v_cvt_pk_bf16_f32 v137, v138, v139
	global_store_dwordx2 v224, v[136:137], s[100:101] offset:32
	v_pk_mul_f32 v[140:141], v[40:41], v[198:199] op_sel_hi:[1,0]
	v_pk_mul_f32 v[142:143], v[42:43], v[198:199] op_sel_hi:[1,0]
	v_pk_fma_f32 v[140:141], v[180:181], v[140:141], v[164:165]
	v_pk_fma_f32 v[142:143], v[182:183], v[142:143], v[166:167]
	v_cvt_pk_bf16_f32 v140, v140, v141
	v_cvt_pk_bf16_f32 v141, v142, v143
	global_store_dwordx2 v224, v[140:141], s[100:101] offset:256
	v_pk_mul_f32 v[144:145], v[36:37], v[198:199] op_sel_hi:[1,0]
	v_pk_mul_f32 v[146:147], v[38:39], v[198:199] op_sel_hi:[1,0]
	v_pk_fma_f32 v[144:145], v[184:185], v[144:145], v[168:169]
	v_pk_fma_f32 v[146:147], v[186:187], v[146:147], v[170:171]
	v_cvt_pk_bf16_f32 v144, v144, v145
	v_cvt_pk_bf16_f32 v145, v146, v147
	global_store_dwordx2 v224, v[144:145], s[100:101] offset:288
	v_add_u32_e32 v224, 0x8000, v224
	global_store_dwordx4 v225, v[32:35], s[4:5]
	global_store_dwordx4 v225, v[28:31], s[4:5] offset:64
	global_store_dwordx4 v225, v[24:27], s[4:5] offset:512
	global_store_dwordx4 v225, v[20:23], s[4:5] offset:576
	v_add_u32_e32 v225, 0x10000, v225
	v_pk_mul_f32 v[132:133], v[32:33], v[200:201] op_sel_hi:[1,0]
	v_pk_mul_f32 v[134:135], v[34:35], v[200:201] op_sel_hi:[1,0]
	v_pk_fma_f32 v[132:133], v[172:173], v[132:133], v[156:157]
	v_pk_fma_f32 v[134:135], v[174:175], v[134:135], v[158:159]
	v_cvt_pk_bf16_f32 v132, v132, v133
	v_cvt_pk_bf16_f32 v133, v134, v135
	global_store_dwordx2 v224, v[132:133], s[100:101]
	v_pk_mul_f32 v[136:137], v[28:29], v[200:201] op_sel_hi:[1,0]
	v_pk_mul_f32 v[138:139], v[30:31], v[200:201] op_sel_hi:[1,0]
	v_pk_fma_f32 v[136:137], v[176:177], v[136:137], v[160:161]
	v_pk_fma_f32 v[138:139], v[178:179], v[138:139], v[162:163]
	v_cvt_pk_bf16_f32 v136, v136, v137
	v_cvt_pk_bf16_f32 v137, v138, v139
	global_store_dwordx2 v224, v[136:137], s[100:101] offset:32
	v_pk_mul_f32 v[140:141], v[24:25], v[200:201] op_sel_hi:[1,0]
	v_pk_mul_f32 v[142:143], v[26:27], v[200:201] op_sel_hi:[1,0]
	v_pk_fma_f32 v[140:141], v[180:181], v[140:141], v[164:165]
	v_pk_fma_f32 v[142:143], v[182:183], v[142:143], v[166:167]
	v_cvt_pk_bf16_f32 v140, v140, v141
	v_cvt_pk_bf16_f32 v141, v142, v143
	global_store_dwordx2 v224, v[140:141], s[100:101] offset:256
	v_pk_mul_f32 v[144:145], v[20:21], v[200:201] op_sel_hi:[1,0]
	v_pk_mul_f32 v[146:147], v[22:23], v[200:201] op_sel_hi:[1,0]
	v_pk_fma_f32 v[144:145], v[184:185], v[144:145], v[168:169]
	v_pk_fma_f32 v[146:147], v[186:187], v[146:147], v[170:171]
	v_cvt_pk_bf16_f32 v144, v144, v145
	v_cvt_pk_bf16_f32 v145, v146, v147
	global_store_dwordx2 v224, v[144:145], s[100:101] offset:288
	v_add_u32_e32 v224, 0x8000, v224
	global_store_dwordx4 v225, v[16:19], s[4:5]
	global_store_dwordx4 v225, v[8:11], s[4:5] offset:64
	global_store_dwordx4 v225, v[4:7], s[4:5] offset:512
	global_store_dwordx4 v225, v[0:3], s[4:5] offset:576
	v_pk_mul_f32 v[132:133], v[16:17], v[202:203] op_sel_hi:[1,0]
	v_pk_mul_f32 v[134:135], v[18:19], v[202:203] op_sel_hi:[1,0]
	v_pk_fma_f32 v[132:133], v[172:173], v[132:133], v[156:157]
	v_pk_fma_f32 v[134:135], v[174:175], v[134:135], v[158:159]
	v_cvt_pk_bf16_f32 v132, v132, v133
	v_cvt_pk_bf16_f32 v133, v134, v135
	global_store_dwordx2 v224, v[132:133], s[100:101]
	v_pk_mul_f32 v[136:137], v[8:9], v[202:203] op_sel_hi:[1,0]
	v_pk_mul_f32 v[138:139], v[10:11], v[202:203] op_sel_hi:[1,0]
	v_pk_fma_f32 v[136:137], v[176:177], v[136:137], v[160:161]
	v_pk_fma_f32 v[138:139], v[178:179], v[138:139], v[162:163]
	v_cvt_pk_bf16_f32 v136, v136, v137
	v_cvt_pk_bf16_f32 v137, v138, v139
	global_store_dwordx2 v224, v[136:137], s[100:101] offset:32
	v_pk_mul_f32 v[140:141], v[4:5], v[202:203] op_sel_hi:[1,0]
	v_pk_mul_f32 v[142:143], v[6:7], v[202:203] op_sel_hi:[1,0]
	v_pk_fma_f32 v[140:141], v[180:181], v[140:141], v[164:165]
	v_pk_fma_f32 v[142:143], v[182:183], v[142:143], v[166:167]
	v_cvt_pk_bf16_f32 v140, v140, v141
	v_cvt_pk_bf16_f32 v141, v142, v143
	global_store_dwordx2 v224, v[140:141], s[100:101] offset:256
	v_pk_mul_f32 v[144:145], v[0:1], v[202:203] op_sel_hi:[1,0]
	v_pk_mul_f32 v[146:147], v[2:3], v[202:203] op_sel_hi:[1,0]
	v_pk_fma_f32 v[144:145], v[184:185], v[144:145], v[168:169]
	v_pk_fma_f32 v[146:147], v[186:187], v[146:147], v[170:171]
	v_cvt_pk_bf16_f32 v144, v144, v145
	v_cvt_pk_bf16_f32 v145, v146, v147
	global_store_dwordx2 v224, v[144:145], s[100:101] offset:288
	s_mov_b64 s[22:23], 0
	s_branch .LBB0_970
